# phase0 w_up gain loads de-serialized; phase2 scoring drops redundant canonicalizing max before relu
# speedup vs baseline: 1.0123x; 1.0123x over previous
; __device__ __forceinline__ void tconv_wave(const float* __restrict__ src, int ldsrc, int k0, int nsrc0, int nvalid,
;                                            u16* __restrict__ dst, int K, int ndst0, const float* __restrict__ gain, float* smw, int lane, int permg) {
; #pragma unroll 1
;   for (int kb = 0; kb < 64; kb += 32) {
;     float v[32];
; #pragma unroll
;     for (int i = 0; i < 32; i++) {
;       float t = 0.f;
;       if (lane < nvalid) {
;         t = src[(size_t)(k0 + kb + i) * ldsrc + nsrc0 + lane];
;         if (gain) t *= gain[k0 + kb + i];
;       }
;       v[i] = t;
;     }
; #pragma unroll
;     for (int i = 0; i < 32; i++) smw[(kb + i) * 65 + lane] = v[i];
.LBB0_31:
	s_or_b64 exec, exec, s[42:43]
	s_mulk_i32 s35, 0x104
	v_add_u32_e32 v6, s35, v13
	s_waitcnt vmcnt(0)
	s_and_b64 s[44:45], s[6:7], s[38:39]
	s_and_saveexec_b64 s[98:99], s[44:45]
	s_cbranch_execz .Lp0_nogain
	v_mul_f32_e32 v5, v5, v64
	v_mul_f32_e32 v3, v3, v65
	v_mul_f32_e32 v29, v29, v66
	v_mul_f32_e32 v28, v28, v67
	v_mul_f32_e32 v31, v31, v68
	v_mul_f32_e32 v30, v30, v69
	v_mul_f32_e32 v33, v33, v70
	v_mul_f32_e32 v32, v32, v71
	v_mul_f32_e32 v36, v36, v72
	v_mul_f32_e32 v35, v35, v73
	v_mul_f32_e32 v38, v38, v74
	v_mul_f32_e32 v37, v37, v75
	v_mul_f32_e32 v40, v40, v76
	v_mul_f32_e32 v39, v39, v77
	v_mul_f32_e32 v42, v42, v78
	v_mul_f32_e32 v41, v41, v79
	v_mul_f32_e32 v44, v44, v80
	v_mul_f32_e32 v43, v43, v81
	v_mul_f32_e32 v46, v46, v82
	v_mul_f32_e32 v45, v45, v83
	v_mul_f32_e32 v48, v48, v84
	v_mul_f32_e32 v47, v47, v85
	v_mul_f32_e32 v50, v50, v86
	v_mul_f32_e32 v49, v49, v87
	v_mul_f32_e32 v52, v52, v88
	v_mul_f32_e32 v51, v51, v89
	v_mul_f32_e32 v54, v54, v90
	v_mul_f32_e32 v53, v53, v91
	v_mul_f32_e32 v56, v56, v92
	v_mul_f32_e32 v55, v55, v93
	v_mul_f32_e32 v58, v58, v94
	v_mul_f32_e32 v57, v57, v95
.Lp0_nogain:
	s_mov_b64 exec, s[98:99]
	ds_write2_b32 v6, v5, v3 offset1:65
	ds_write2_b32 v6, v29, v28 offset0:130 offset1:195
	v_add_u32_e32 v3, 0x400, v6
	ds_write2_b32 v3, v31, v30 offset0:4 offset1:69
	ds_write2_b32 v3, v33, v32 offset0:134 offset1:199
	v_add_u32_e32 v3, 0x800, v6
	ds_write2_b32 v3, v36, v35 offset0:8 offset1:73
	ds_write2_b32 v3, v38, v37 offset0:138 offset1:203
	v_add_u32_e32 v3, 0xc00, v6
	ds_write2_b32 v3, v40, v39 offset0:12 offset1:77
	ds_write2_b32 v3, v42, v41 offset0:142 offset1:207
	v_add_u32_e32 v3, 0x1000, v6
	ds_write2_b32 v3, v44, v43 offset0:16 offset1:81
	ds_write2_b32 v3, v46, v45 offset0:146 offset1:211
	v_add_u32_e32 v3, 0x1400, v6
	s_xor_b64 s[42:43], s[40:41], -1
	ds_write2_b32 v3, v48, v47 offset0:20 offset1:85
	ds_write2_b32 v3, v50, v49 offset0:150 offset1:215
	v_add_u32_e32 v3, 0x1800, v6
	ds_write2_b32 v3, v52, v51 offset0:24 offset1:89
	ds_write2_b32 v3, v54, v53 offset0:154 offset1:219
	v_add_u32_e32 v3, 0x1c00, v6
	s_mov_b32 s35, 32
	s_mov_b64 s[40:41], 0
	s_and_b64 vcc, exec, s[42:43]
	ds_write2_b32 v3, v56, v55 offset0:28 offset1:93
	ds_write2_b32 v3, v58, v57 offset0:158 offset1:223
	s_cbranch_vccnz .LBB0_159
.LBB0_32:
	v_or_b32_e32 v22, s35, v2
	v_ashrrev_i32_e32 v23, 31, v22
	v_mov_b32_e32 v3, 0
	v_mul_lo_u32 v6, v16, v23
	v_mov_b32_e32 v5, 0
	s_and_saveexec_b64 s[42:43], s[38:39]
	s_cbranch_execz .LBB0_36
	v_mul_lo_u32 v5, v17, v22
	v_mad_u64_u32 v[28:29], s[44:45], v16, v22, 0
	v_add3_u32 v29, v29, v6, v5
	v_lshl_add_u64 v[28:29], v[28:29], 2, v[20:21]
	global_load_dword v5, v[28:29], off
	s_and_saveexec_b64 s[44:45], s[6:7]
	s_cbranch_execz .LBB0_35
	v_lshl_add_u64 v[28:29], v[22:23], 2, v[14:15]
	global_load_dword v64, v[28:29], off

; __device__ __forceinline__ void tconv_wave(const float* __restrict__ src, int ldsrc, int k0, int nsrc0, int nvalid,
;                                            u16* __restrict__ dst, int K, int ndst0, const float* __restrict__ gain, float* smw, int lane, int permg) {
;     ...
;     for (int i = 0; i < 32; i++) {
;       float t = 0.f;
;       if (lane < nvalid) {
;         t = src[(size_t)(k0 + kb + i) * ldsrc + nsrc0 + lane];
;         if (gain) t *= gain[k0 + kb + i];
;       }
;       v[i] = t;
;     }
.LBB0_36:
	s_or_b64 exec, exec, s[42:43]
	s_and_saveexec_b64 s[42:43], s[38:39]
	s_cbranch_execz .LBB0_40
	v_or_b32_e32 v3, 1, v22
	v_mul_lo_u32 v30, v17, v3
	v_mad_u64_u32 v[28:29], s[44:45], v16, v3, 0
	v_add3_u32 v29, v29, v6, v30
	v_lshl_add_u64 v[28:29], v[28:29], 2, v[20:21]
	global_load_dword v3, v[28:29], off
	s_and_saveexec_b64 s[44:45], s[6:7]
	s_cbranch_execz .LBB0_39
	v_lshl_add_u64 v[28:29], v[22:23], 2, v[14:15]
	global_load_dword v65, v[28:29], off offset:4

; __device__ __forceinline__ void tconv_wave(const float* __restrict__ src, int ldsrc, int k0, int nsrc0, int nvalid,
;                                            u16* __restrict__ dst, int K, int ndst0, const float* __restrict__ gain, float* smw, int lane, int permg) {
;     ...
;     for (int i = 0; i < 32; i++) {
;       float t = 0.f;
;       if (lane < nvalid) {
;         t = src[(size_t)(k0 + kb + i) * ldsrc + nsrc0 + lane];
;         if (gain) t *= gain[k0 + kb + i];
;       }
;       v[i] = t;
;     }
.LBB0_40:
	s_or_b64 exec, exec, s[42:43]
	v_mov_b32_e32 v28, 0
	v_mov_b32_e32 v29, 0
	s_and_saveexec_b64 s[42:43], s[38:39]
	s_cbranch_execz .LBB0_44
	v_or_b32_e32 v29, 2, v22
	v_mul_lo_u32 v32, v17, v29
	v_mad_u64_u32 v[30:31], s[44:45], v16, v29, 0
	v_add3_u32 v31, v31, v6, v32
	v_lshl_add_u64 v[30:31], v[30:31], 2, v[20:21]
	global_load_dword v29, v[30:31], off
	s_and_saveexec_b64 s[44:45], s[6:7]
	s_cbranch_execz .LBB0_43
	v_lshl_add_u64 v[30:31], v[22:23], 2, v[14:15]
	global_load_dword v66, v[30:31], off offset:8

; __device__ __forceinline__ void tconv_wave(const float* __restrict__ src, int ldsrc, int k0, int nsrc0, int nvalid,
;                                            u16* __restrict__ dst, int K, int ndst0, const float* __restrict__ gain, float* smw, int lane, int permg) {
;     ...
;     for (int i = 0; i < 32; i++) {
;       float t = 0.f;
;       if (lane < nvalid) {
;         t = src[(size_t)(k0 + kb + i) * ldsrc + nsrc0 + lane];
;         if (gain) t *= gain[k0 + kb + i];
;       }
;       v[i] = t;
;     }
.LBB0_44:
	s_or_b64 exec, exec, s[42:43]
	s_and_saveexec_b64 s[42:43], s[38:39]
	s_cbranch_execz .LBB0_48
	v_or_b32_e32 v28, 3, v22
	v_mul_lo_u32 v32, v17, v28
	v_mad_u64_u32 v[30:31], s[44:45], v16, v28, 0
	v_add3_u32 v31, v31, v6, v32
	v_lshl_add_u64 v[30:31], v[30:31], 2, v[20:21]
	global_load_dword v28, v[30:31], off
	s_and_saveexec_b64 s[44:45], s[6:7]
	s_cbranch_execz .LBB0_47
	v_lshl_add_u64 v[30:31], v[22:23], 2, v[14:15]
	global_load_dword v67, v[30:31], off offset:12

; __device__ __forceinline__ void tconv_wave(const float* __restrict__ src, int ldsrc, int k0, int nsrc0, int nvalid,
;                                            u16* __restrict__ dst, int K, int ndst0, const float* __restrict__ gain, float* smw, int lane, int permg) {
;     ...
;     for (int i = 0; i < 32; i++) {
;       float t = 0.f;
;       if (lane < nvalid) {
;         t = src[(size_t)(k0 + kb + i) * ldsrc + nsrc0 + lane];
;         if (gain) t *= gain[k0 + kb + i];
;       }
;       v[i] = t;
;     }
.LBB0_48:
	s_or_b64 exec, exec, s[42:43]
	v_mov_b32_e32 v30, 0
	v_mov_b32_e32 v31, 0
	s_and_saveexec_b64 s[42:43], s[38:39]
	s_cbranch_execz .LBB0_52
	v_or_b32_e32 v31, 4, v22
	v_mul_lo_u32 v35, v17, v31
	v_mad_u64_u32 v[32:33], s[44:45], v16, v31, 0
	v_add3_u32 v33, v33, v6, v35
	v_lshl_add_u64 v[32:33], v[32:33], 2, v[20:21]
	global_load_dword v31, v[32:33], off
	s_and_saveexec_b64 s[44:45], s[6:7]
	s_cbranch_execz .LBB0_51
	v_lshl_add_u64 v[32:33], v[22:23], 2, v[14:15]
	global_load_dword v68, v[32:33], off offset:16

; __device__ __forceinline__ void tconv_wave(const float* __restrict__ src, int ldsrc, int k0, int nsrc0, int nvalid,
;                                            u16* __restrict__ dst, int K, int ndst0, const float* __restrict__ gain, float* smw, int lane, int permg) {
;     ...
;     for (int i = 0; i < 32; i++) {
;       float t = 0.f;
;       if (lane < nvalid) {
;         t = src[(size_t)(k0 + kb + i) * ldsrc + nsrc0 + lane];
;         if (gain) t *= gain[k0 + kb + i];
;       }
;       v[i] = t;
;     }
.LBB0_52:
	s_or_b64 exec, exec, s[42:43]
	s_and_saveexec_b64 s[42:43], s[38:39]
	s_cbranch_execz .LBB0_56
	v_or_b32_e32 v30, 5, v22
	v_mul_lo_u32 v35, v17, v30
	v_mad_u64_u32 v[32:33], s[44:45], v16, v30, 0
	v_add3_u32 v33, v33, v6, v35
	v_lshl_add_u64 v[32:33], v[32:33], 2, v[20:21]
	global_load_dword v30, v[32:33], off
	s_and_saveexec_b64 s[44:45], s[6:7]
	s_cbranch_execz .LBB0_55
	v_lshl_add_u64 v[32:33], v[22:23], 2, v[14:15]
	global_load_dword v69, v[32:33], off offset:20

; __device__ __forceinline__ void tconv_wave(const float* __restrict__ src, int ldsrc, int k0, int nsrc0, int nvalid,
;                                            u16* __restrict__ dst, int K, int ndst0, const float* __restrict__ gain, float* smw, int lane, int permg) {
;     ...
;     for (int i = 0; i < 32; i++) {
;       float t = 0.f;
;       if (lane < nvalid) {
;         t = src[(size_t)(k0 + kb + i) * ldsrc + nsrc0 + lane];
;         if (gain) t *= gain[k0 + kb + i];
;       }
;       v[i] = t;
;     }
.LBB0_56:
	s_or_b64 exec, exec, s[42:43]
	v_mov_b32_e32 v32, 0
	v_mov_b32_e32 v33, 0
	s_and_saveexec_b64 s[42:43], s[38:39]
	s_cbranch_execz .LBB0_60
	v_or_b32_e32 v33, 6, v22
	v_mul_lo_u32 v35, v17, v33
	v_mad_u64_u32 v[36:37], s[44:45], v16, v33, 0
	v_add3_u32 v37, v37, v6, v35
	v_lshl_add_u64 v[36:37], v[36:37], 2, v[20:21]
	global_load_dword v33, v[36:37], off
	s_and_saveexec_b64 s[44:45], s[6:7]
	s_cbranch_execz .LBB0_59
	v_lshl_add_u64 v[36:37], v[22:23], 2, v[14:15]
	global_load_dword v70, v[36:37], off offset:24

; __device__ __forceinline__ void tconv_wave(const float* __restrict__ src, int ldsrc, int k0, int nsrc0, int nvalid,
;                                            u16* __restrict__ dst, int K, int ndst0, const float* __restrict__ gain, float* smw, int lane, int permg) {
;     ...
;     for (int i = 0; i < 32; i++) {
;       float t = 0.f;
;       if (lane < nvalid) {
;         t = src[(size_t)(k0 + kb + i) * ldsrc + nsrc0 + lane];
;         if (gain) t *= gain[k0 + kb + i];
;       }
;       v[i] = t;
;     }
.LBB0_60:
	s_or_b64 exec, exec, s[42:43]
	s_and_saveexec_b64 s[42:43], s[38:39]
	s_cbranch_execz .LBB0_64
	v_or_b32_e32 v32, 7, v22
	v_mul_lo_u32 v35, v17, v32
	v_mad_u64_u32 v[36:37], s[44:45], v16, v32, 0
	v_add3_u32 v37, v37, v6, v35
	v_lshl_add_u64 v[36:37], v[36:37], 2, v[20:21]
	global_load_dword v32, v[36:37], off
	s_and_saveexec_b64 s[44:45], s[6:7]
	s_cbranch_execz .LBB0_63
	v_lshl_add_u64 v[36:37], v[22:23], 2, v[14:15]
	global_load_dword v71, v[36:37], off offset:28

; __device__ __forceinline__ void tconv_wave(const float* __restrict__ src, int ldsrc, int k0, int nsrc0, int nvalid,
;                                            u16* __restrict__ dst, int K, int ndst0, const float* __restrict__ gain, float* smw, int lane, int permg) {
;     ...
;     for (int i = 0; i < 32; i++) {
;       float t = 0.f;
;       if (lane < nvalid) {
;         t = src[(size_t)(k0 + kb + i) * ldsrc + nsrc0 + lane];
;         if (gain) t *= gain[k0 + kb + i];
;       }
;       v[i] = t;
;     }
.LBB0_64:
	s_or_b64 exec, exec, s[42:43]
	v_mov_b32_e32 v35, 0
	v_mov_b32_e32 v36, 0
	s_and_saveexec_b64 s[42:43], s[38:39]
	s_cbranch_execz .LBB0_68
	v_or_b32_e32 v36, 8, v22
	v_mul_lo_u32 v38, v17, v36
	v_mad_u64_u32 v[36:37], s[44:45], v16, v36, 0
	v_add3_u32 v37, v37, v6, v38
	v_lshl_add_u64 v[36:37], v[36:37], 2, v[20:21]
	global_load_dword v36, v[36:37], off
	s_and_saveexec_b64 s[44:45], s[6:7]
	s_cbranch_execz .LBB0_67
	v_lshl_add_u64 v[38:39], v[22:23], 2, v[14:15]
	global_load_dword v72, v[38:39], off offset:32

; __device__ __forceinline__ void tconv_wave(const float* __restrict__ src, int ldsrc, int k0, int nsrc0, int nvalid,
;                                            u16* __restrict__ dst, int K, int ndst0, const float* __restrict__ gain, float* smw, int lane, int permg) {
;     ...
;     for (int i = 0; i < 32; i++) {
;       float t = 0.f;
;       if (lane < nvalid) {
;         t = src[(size_t)(k0 + kb + i) * ldsrc + nsrc0 + lane];
;         if (gain) t *= gain[k0 + kb + i];
;       }
;       v[i] = t;
;     }
.LBB0_68:
	s_or_b64 exec, exec, s[42:43]
	s_and_saveexec_b64 s[42:43], s[38:39]
	s_cbranch_execz .LBB0_72
	v_or_b32_e32 v35, 9, v22
	v_mul_lo_u32 v37, v17, v35
	v_mad_u64_u32 v[38:39], s[44:45], v16, v35, 0
	v_add3_u32 v39, v39, v6, v37
	v_lshl_add_u64 v[38:39], v[38:39], 2, v[20:21]
	global_load_dword v35, v[38:39], off
	s_and_saveexec_b64 s[44:45], s[6:7]
	s_cbranch_execz .LBB0_71
	v_lshl_add_u64 v[38:39], v[22:23], 2, v[14:15]
	global_load_dword v73, v[38:39], off offset:36

; __device__ __forceinline__ void tconv_wave(const float* __restrict__ src, int ldsrc, int k0, int nsrc0, int nvalid,
;                                            u16* __restrict__ dst, int K, int ndst0, const float* __restrict__ gain, float* smw, int lane, int permg) {
;     ...
;     for (int i = 0; i < 32; i++) {
;       float t = 0.f;
;       if (lane < nvalid) {
;         t = src[(size_t)(k0 + kb + i) * ldsrc + nsrc0 + lane];
;         if (gain) t *= gain[k0 + kb + i];
;       }
;       v[i] = t;
;     }
.LBB0_72:
	s_or_b64 exec, exec, s[42:43]
	v_mov_b32_e32 v37, 0
	v_mov_b32_e32 v38, 0
	s_and_saveexec_b64 s[42:43], s[38:39]
	s_cbranch_execz .LBB0_76
	v_or_b32_e32 v38, 10, v22
	v_mul_lo_u32 v40, v17, v38
	v_mad_u64_u32 v[38:39], s[44:45], v16, v38, 0
	v_add3_u32 v39, v39, v6, v40
	v_lshl_add_u64 v[38:39], v[38:39], 2, v[20:21]
	global_load_dword v38, v[38:39], off
	s_and_saveexec_b64 s[44:45], s[6:7]
	s_cbranch_execz .LBB0_75
	v_lshl_add_u64 v[40:41], v[22:23], 2, v[14:15]
	global_load_dword v74, v[40:41], off offset:40

; __device__ __forceinline__ void tconv_wave(const float* __restrict__ src, int ldsrc, int k0, int nsrc0, int nvalid,
;                                            u16* __restrict__ dst, int K, int ndst0, const float* __restrict__ gain, float* smw, int lane, int permg) {
;     ...
;     for (int i = 0; i < 32; i++) {
;       float t = 0.f;
;       if (lane < nvalid) {
;         t = src[(size_t)(k0 + kb + i) * ldsrc + nsrc0 + lane];
;         if (gain) t *= gain[k0 + kb + i];
;       }
;       v[i] = t;
;     }
.LBB0_76:
	s_or_b64 exec, exec, s[42:43]
	s_and_saveexec_b64 s[42:43], s[38:39]
	s_cbranch_execz .LBB0_80
	v_or_b32_e32 v37, 11, v22
	v_mul_lo_u32 v39, v17, v37
	v_mad_u64_u32 v[40:41], s[44:45], v16, v37, 0
	v_add3_u32 v41, v41, v6, v39
	v_lshl_add_u64 v[40:41], v[40:41], 2, v[20:21]
	global_load_dword v37, v[40:41], off
	s_and_saveexec_b64 s[44:45], s[6:7]
	s_cbranch_execz .LBB0_79
	v_lshl_add_u64 v[40:41], v[22:23], 2, v[14:15]
	global_load_dword v75, v[40:41], off offset:44

; __device__ __forceinline__ void tconv_wave(const float* __restrict__ src, int ldsrc, int k0, int nsrc0, int nvalid,
;                                            u16* __restrict__ dst, int K, int ndst0, const float* __restrict__ gain, float* smw, int lane, int permg) {
;     ...
;     for (int i = 0; i < 32; i++) {
;       float t = 0.f;
;       if (lane < nvalid) {
;         t = src[(size_t)(k0 + kb + i) * ldsrc + nsrc0 + lane];
;         if (gain) t *= gain[k0 + kb + i];
;       }
;       v[i] = t;
;     }
.LBB0_80:
	s_or_b64 exec, exec, s[42:43]
	v_mov_b32_e32 v39, 0
	v_mov_b32_e32 v40, 0
	s_and_saveexec_b64 s[42:43], s[38:39]
	s_cbranch_execz .LBB0_84
	v_or_b32_e32 v40, 12, v22
	v_mul_lo_u32 v42, v17, v40
	v_mad_u64_u32 v[40:41], s[44:45], v16, v40, 0
	v_add3_u32 v41, v41, v6, v42
	v_lshl_add_u64 v[40:41], v[40:41], 2, v[20:21]
	global_load_dword v40, v[40:41], off
	s_and_saveexec_b64 s[44:45], s[6:7]
	s_cbranch_execz .LBB0_83
	v_lshl_add_u64 v[42:43], v[22:23], 2, v[14:15]
	global_load_dword v76, v[42:43], off offset:48

; __device__ __forceinline__ void tconv_wave(const float* __restrict__ src, int ldsrc, int k0, int nsrc0, int nvalid,
;                                            u16* __restrict__ dst, int K, int ndst0, const float* __restrict__ gain, float* smw, int lane, int permg) {
;     ...
;     for (int i = 0; i < 32; i++) {
;       float t = 0.f;
;       if (lane < nvalid) {
;         t = src[(size_t)(k0 + kb + i) * ldsrc + nsrc0 + lane];
;         if (gain) t *= gain[k0 + kb + i];
;       }
;       v[i] = t;
;     }
.LBB0_84:
	s_or_b64 exec, exec, s[42:43]
	s_and_saveexec_b64 s[42:43], s[38:39]
	s_cbranch_execz .LBB0_88
	v_or_b32_e32 v39, 13, v22
	v_mul_lo_u32 v41, v17, v39
	v_mad_u64_u32 v[42:43], s[44:45], v16, v39, 0
	v_add3_u32 v43, v43, v6, v41
	v_lshl_add_u64 v[42:43], v[42:43], 2, v[20:21]
	global_load_dword v39, v[42:43], off
	s_and_saveexec_b64 s[44:45], s[6:7]
	s_cbranch_execz .LBB0_87
	v_lshl_add_u64 v[42:43], v[22:23], 2, v[14:15]
	global_load_dword v77, v[42:43], off offset:52

; __device__ __forceinline__ void tconv_wave(const float* __restrict__ src, int ldsrc, int k0, int nsrc0, int nvalid,
;                                            u16* __restrict__ dst, int K, int ndst0, const float* __restrict__ gain, float* smw, int lane, int permg) {
;     ...
;   for (int kb = 0; kb < 64; kb += 32) {
;     float v[32];
; #pragma unroll
;     for (int i = 0; i < 32; i++) {
;       float t = 0.f;
;       if (lane < nvalid) {
;         t = src[(size_t)(k0 + kb + i) * ldsrc + nsrc0 + lane];
;         if (gain) t *= gain[k0 + kb + i];
;       }
;       v[i] = t;
;     }
; #pragma unroll
;     for (int i = 0; i < 32; i++) smw[(kb + i) * 65 + lane] = v[i];
.LBB0_88:
	s_or_b64 exec, exec, s[42:43]
	v_mov_b32_e32 v41, 0
	v_mov_b32_e32 v42, 0
	s_and_saveexec_b64 s[42:43], s[38:39]
	s_cbranch_execz .LBB0_92
	v_or_b32_e32 v42, 14, v22
	v_mul_lo_u32 v44, v17, v42
	v_mad_u64_u32 v[42:43], s[44:45], v16, v42, 0
	v_add3_u32 v43, v43, v6, v44
	v_lshl_add_u64 v[42:43], v[42:43], 2, v[20:21]
	global_load_dword v42, v[42:43], off
	s_and_saveexec_b64 s[44:45], s[6:7]
	s_cbranch_execz .LBB0_91
	v_lshl_add_u64 v[44:45], v[22:23], 2, v[14:15]
	global_load_dword v78, v[44:45], off offset:56

; __device__ __forceinline__ void tconv_wave(const float* __restrict__ src, int ldsrc, int k0, int nsrc0, int nvalid,
;                                            u16* __restrict__ dst, int K, int ndst0, const float* __restrict__ gain, float* smw, int lane, int permg) {
;     ...
;   for (int kb = 0; kb < 64; kb += 32) {
;     float v[32];
; #pragma unroll
;     for (int i = 0; i < 32; i++) {
;       float t = 0.f;
;       if (lane < nvalid) {
;         t = src[(size_t)(k0 + kb + i) * ldsrc + nsrc0 + lane];
;         if (gain) t *= gain[k0 + kb + i];
;       }
;       v[i] = t;
;     }
; #pragma unroll
;     for (int i = 0; i < 32; i++) smw[(kb + i) * 65 + lane] = v[i];
.LBB0_92:
	s_or_b64 exec, exec, s[42:43]
	s_and_saveexec_b64 s[42:43], s[38:39]
	s_cbranch_execz .LBB0_96
	v_or_b32_e32 v41, 15, v22
	v_mul_lo_u32 v43, v17, v41
	v_mad_u64_u32 v[44:45], s[44:45], v16, v41, 0
	v_add3_u32 v45, v45, v6, v43
	v_lshl_add_u64 v[44:45], v[44:45], 2, v[20:21]
	global_load_dword v41, v[44:45], off
	s_and_saveexec_b64 s[44:45], s[6:7]
	s_cbranch_execz .LBB0_95
	v_lshl_add_u64 v[44:45], v[22:23], 2, v[14:15]
	global_load_dword v79, v[44:45], off offset:60

; __device__ __forceinline__ void tconv_wave(const float* __restrict__ src, int ldsrc, int k0, int nsrc0, int nvalid,
;                                            u16* __restrict__ dst, int K, int ndst0, const float* __restrict__ gain, float* smw, int lane, int permg) {
;     ...
;   for (int kb = 0; kb < 64; kb += 32) {
;     float v[32];
; #pragma unroll
;     for (int i = 0; i < 32; i++) {
;       float t = 0.f;
;       if (lane < nvalid) {
;         t = src[(size_t)(k0 + kb + i) * ldsrc + nsrc0 + lane];
;         if (gain) t *= gain[k0 + kb + i];
;       }
;       v[i] = t;
;     }
; #pragma unroll
;     for (int i = 0; i < 32; i++) smw[(kb + i) * 65 + lane] = v[i];
.LBB0_96:
	s_or_b64 exec, exec, s[42:43]
	v_mov_b32_e32 v43, 0
	v_mov_b32_e32 v44, 0
	s_and_saveexec_b64 s[42:43], s[38:39]
	s_cbranch_execz .LBB0_100
	v_or_b32_e32 v44, 16, v22
	v_mul_lo_u32 v46, v17, v44
	v_mad_u64_u32 v[44:45], s[44:45], v16, v44, 0
	v_add3_u32 v45, v45, v6, v46
	v_lshl_add_u64 v[44:45], v[44:45], 2, v[20:21]
	global_load_dword v44, v[44:45], off
	s_and_saveexec_b64 s[44:45], s[6:7]
	s_cbranch_execz .LBB0_99
	v_lshl_add_u64 v[46:47], v[22:23], 2, v[14:15]
	global_load_dword v80, v[46:47], off offset:64

; __device__ __forceinline__ void tconv_wave(const float* __restrict__ src, int ldsrc, int k0, int nsrc0, int nvalid,
;                                            u16* __restrict__ dst, int K, int ndst0, const float* __restrict__ gain, float* smw, int lane, int permg) {
;     ...
;   for (int kb = 0; kb < 64; kb += 32) {
;     float v[32];
; #pragma unroll
;     for (int i = 0; i < 32; i++) {
;       float t = 0.f;
;       if (lane < nvalid) {
;         t = src[(size_t)(k0 + kb + i) * ldsrc + nsrc0 + lane];
;         if (gain) t *= gain[k0 + kb + i];
;       }
;       v[i] = t;
;     }
; #pragma unroll
;     for (int i = 0; i < 32; i++) smw[(kb + i) * 65 + lane] = v[i];
.LBB0_100:
	s_or_b64 exec, exec, s[42:43]
	s_and_saveexec_b64 s[42:43], s[38:39]
	s_cbranch_execz .LBB0_104
	v_or_b32_e32 v43, 17, v22
	v_mul_lo_u32 v45, v17, v43
	v_mad_u64_u32 v[46:47], s[44:45], v16, v43, 0
	v_add3_u32 v47, v47, v6, v45
	v_lshl_add_u64 v[46:47], v[46:47], 2, v[20:21]
	global_load_dword v43, v[46:47], off
	s_and_saveexec_b64 s[44:45], s[6:7]
	s_cbranch_execz .LBB0_103
	v_lshl_add_u64 v[46:47], v[22:23], 2, v[14:15]
	global_load_dword v81, v[46:47], off offset:68

; __device__ __forceinline__ void tconv_wave(const float* __restrict__ src, int ldsrc, int k0, int nsrc0, int nvalid,
;                                            u16* __restrict__ dst, int K, int ndst0, const float* __restrict__ gain, float* smw, int lane, int permg) {
;     ...
;   for (int kb = 0; kb < 64; kb += 32) {
;     float v[32];
; #pragma unroll
;     for (int i = 0; i < 32; i++) {
;       float t = 0.f;
;       if (lane < nvalid) {
;         t = src[(size_t)(k0 + kb + i) * ldsrc + nsrc0 + lane];
;         if (gain) t *= gain[k0 + kb + i];
;       }
;       v[i] = t;
;     }
; #pragma unroll
;     for (int i = 0; i < 32; i++) smw[(kb + i) * 65 + lane] = v[i];
.LBB0_104:
	s_or_b64 exec, exec, s[42:43]
	v_mov_b32_e32 v45, 0
	v_mov_b32_e32 v46, 0
	s_and_saveexec_b64 s[42:43], s[38:39]
	s_cbranch_execz .LBB0_108
	v_or_b32_e32 v46, 18, v22
	v_mul_lo_u32 v48, v17, v46
	v_mad_u64_u32 v[46:47], s[44:45], v16, v46, 0
	v_add3_u32 v47, v47, v6, v48
	v_lshl_add_u64 v[46:47], v[46:47], 2, v[20:21]
	global_load_dword v46, v[46:47], off
	s_and_saveexec_b64 s[44:45], s[6:7]
	s_cbranch_execz .LBB0_107
	v_lshl_add_u64 v[48:49], v[22:23], 2, v[14:15]
	global_load_dword v82, v[48:49], off offset:72

; __device__ __forceinline__ void tconv_wave(const float* __restrict__ src, int ldsrc, int k0, int nsrc0, int nvalid,
;                                            u16* __restrict__ dst, int K, int ndst0, const float* __restrict__ gain, float* smw, int lane, int permg) {
;     ...
;   for (int kb = 0; kb < 64; kb += 32) {
;     float v[32];
; #pragma unroll
;     for (int i = 0; i < 32; i++) {
;       float t = 0.f;
;       if (lane < nvalid) {
;         t = src[(size_t)(k0 + kb + i) * ldsrc + nsrc0 + lane];
;         if (gain) t *= gain[k0 + kb + i];
;       }
;       v[i] = t;
;     }
; #pragma unroll
;     for (int i = 0; i < 32; i++) smw[(kb + i) * 65 + lane] = v[i];
.LBB0_108:
	s_or_b64 exec, exec, s[42:43]
	s_and_saveexec_b64 s[42:43], s[38:39]
	s_cbranch_execz .LBB0_112
	v_or_b32_e32 v45, 19, v22
	v_mul_lo_u32 v47, v17, v45
	v_mad_u64_u32 v[48:49], s[44:45], v16, v45, 0
	v_add3_u32 v49, v49, v6, v47
	v_lshl_add_u64 v[48:49], v[48:49], 2, v[20:21]
	global_load_dword v45, v[48:49], off
	s_and_saveexec_b64 s[44:45], s[6:7]
	s_cbranch_execz .LBB0_111
	v_lshl_add_u64 v[48:49], v[22:23], 2, v[14:15]
	global_load_dword v83, v[48:49], off offset:76

; __device__ __forceinline__ void tconv_wave(const float* __restrict__ src, int ldsrc, int k0, int nsrc0, int nvalid,
;                                            u16* __restrict__ dst, int K, int ndst0, const float* __restrict__ gain, float* smw, int lane, int permg) {
;     ...
;   for (int kb = 0; kb < 64; kb += 32) {
;     float v[32];
; #pragma unroll
;     for (int i = 0; i < 32; i++) {
;       float t = 0.f;
;       if (lane < nvalid) {
;         t = src[(size_t)(k0 + kb + i) * ldsrc + nsrc0 + lane];
;         if (gain) t *= gain[k0 + kb + i];
;       }
;       v[i] = t;
;     }
; #pragma unroll
;     for (int i = 0; i < 32; i++) smw[(kb + i) * 65 + lane] = v[i];
.LBB0_112:
	s_or_b64 exec, exec, s[42:43]
	v_mov_b32_e32 v47, 0
	v_mov_b32_e32 v48, 0
	s_and_saveexec_b64 s[42:43], s[38:39]
	s_cbranch_execz .LBB0_116
	v_or_b32_e32 v48, 20, v22
	v_mul_lo_u32 v50, v17, v48
	v_mad_u64_u32 v[48:49], s[44:45], v16, v48, 0
	v_add3_u32 v49, v49, v6, v50
	v_lshl_add_u64 v[48:49], v[48:49], 2, v[20:21]
	global_load_dword v48, v[48:49], off
	s_and_saveexec_b64 s[44:45], s[6:7]
	s_cbranch_execz .LBB0_115
	v_lshl_add_u64 v[50:51], v[22:23], 2, v[14:15]
	global_load_dword v84, v[50:51], off offset:80

; __device__ __forceinline__ void tconv_wave(const float* __restrict__ src, int ldsrc, int k0, int nsrc0, int nvalid,
;                                            u16* __restrict__ dst, int K, int ndst0, const float* __restrict__ gain, float* smw, int lane, int permg) {
;     ...
;   for (int kb = 0; kb < 64; kb += 32) {
;     float v[32];
; #pragma unroll
;     for (int i = 0; i < 32; i++) {
;       float t = 0.f;
;       if (lane < nvalid) {
;         t = src[(size_t)(k0 + kb + i) * ldsrc + nsrc0 + lane];
;         if (gain) t *= gain[k0 + kb + i];
;       }
;       v[i] = t;
;     }
; #pragma unroll
;     for (int i = 0; i < 32; i++) smw[(kb + i) * 65 + lane] = v[i];
.LBB0_116:
	s_or_b64 exec, exec, s[42:43]
	s_and_saveexec_b64 s[42:43], s[38:39]
	s_cbranch_execz .LBB0_120
	v_or_b32_e32 v47, 21, v22
	v_mul_lo_u32 v49, v17, v47
	v_mad_u64_u32 v[50:51], s[44:45], v16, v47, 0
	v_add3_u32 v51, v51, v6, v49
	v_lshl_add_u64 v[50:51], v[50:51], 2, v[20:21]
	global_load_dword v47, v[50:51], off
	s_and_saveexec_b64 s[44:45], s[6:7]
	s_cbranch_execz .LBB0_119
	v_lshl_add_u64 v[50:51], v[22:23], 2, v[14:15]
	global_load_dword v85, v[50:51], off offset:84

; __device__ __forceinline__ void tconv_wave(const float* __restrict__ src, int ldsrc, int k0, int nsrc0, int nvalid,
;                                            u16* __restrict__ dst, int K, int ndst0, const float* __restrict__ gain, float* smw, int lane, int permg) {
;     ...
;   for (int kb = 0; kb < 64; kb += 32) {
;     float v[32];
; #pragma unroll
;     for (int i = 0; i < 32; i++) {
;       float t = 0.f;
;       if (lane < nvalid) {
;         t = src[(size_t)(k0 + kb + i) * ldsrc + nsrc0 + lane];
;         if (gain) t *= gain[k0 + kb + i];
;       }
;       v[i] = t;
;     }
; #pragma unroll
;     for (int i = 0; i < 32; i++) smw[(kb + i) * 65 + lane] = v[i];
.LBB0_120:
	s_or_b64 exec, exec, s[42:43]
	v_mov_b32_e32 v49, 0
	v_mov_b32_e32 v50, 0
	s_and_saveexec_b64 s[42:43], s[38:39]
	s_cbranch_execz .LBB0_124
	v_or_b32_e32 v50, 22, v22
	v_mul_lo_u32 v52, v17, v50
	v_mad_u64_u32 v[50:51], s[44:45], v16, v50, 0
	v_add3_u32 v51, v51, v6, v52
	v_lshl_add_u64 v[50:51], v[50:51], 2, v[20:21]
	global_load_dword v50, v[50:51], off
	s_and_saveexec_b64 s[44:45], s[6:7]
	s_cbranch_execz .LBB0_123
	v_lshl_add_u64 v[52:53], v[22:23], 2, v[14:15]
	global_load_dword v86, v[52:53], off offset:88

; __device__ __forceinline__ void tconv_wave(const float* __restrict__ src, int ldsrc, int k0, int nsrc0, int nvalid,
;                                            u16* __restrict__ dst, int K, int ndst0, const float* __restrict__ gain, float* smw, int lane, int permg) {
;     ...
;   for (int kb = 0; kb < 64; kb += 32) {
;     float v[32];
; #pragma unroll
;     for (int i = 0; i < 32; i++) {
;       float t = 0.f;
;       if (lane < nvalid) {
;         t = src[(size_t)(k0 + kb + i) * ldsrc + nsrc0 + lane];
;         if (gain) t *= gain[k0 + kb + i];
;       }
;       v[i] = t;
;     }
; #pragma unroll
;     for (int i = 0; i < 32; i++) smw[(kb + i) * 65 + lane] = v[i];
.LBB0_124:
	s_or_b64 exec, exec, s[42:43]
	s_and_saveexec_b64 s[42:43], s[38:39]
	s_cbranch_execz .LBB0_128
	v_or_b32_e32 v49, 23, v22
	v_mul_lo_u32 v51, v17, v49
	v_mad_u64_u32 v[52:53], s[44:45], v16, v49, 0
	v_add3_u32 v53, v53, v6, v51
	v_lshl_add_u64 v[52:53], v[52:53], 2, v[20:21]
	global_load_dword v49, v[52:53], off
	s_and_saveexec_b64 s[44:45], s[6:7]
	s_cbranch_execz .LBB0_127
	v_lshl_add_u64 v[52:53], v[22:23], 2, v[14:15]
	global_load_dword v87, v[52:53], off offset:92

; __device__ __forceinline__ void tconv_wave(const float* __restrict__ src, int ldsrc, int k0, int nsrc0, int nvalid,
;                                            u16* __restrict__ dst, int K, int ndst0, const float* __restrict__ gain, float* smw, int lane, int permg) {
;     ...
;   for (int kb = 0; kb < 64; kb += 32) {
;     float v[32];
; #pragma unroll
;     for (int i = 0; i < 32; i++) {
;       float t = 0.f;
;       if (lane < nvalid) {
;         t = src[(size_t)(k0 + kb + i) * ldsrc + nsrc0 + lane];
;         if (gain) t *= gain[k0 + kb + i];
;       }
;       v[i] = t;
;     }
; #pragma unroll
;     for (int i = 0; i < 32; i++) smw[(kb + i) * 65 + lane] = v[i];
.LBB0_128:
	s_or_b64 exec, exec, s[42:43]
	v_mov_b32_e32 v51, 0
	v_mov_b32_e32 v52, 0
	s_and_saveexec_b64 s[42:43], s[38:39]
	s_cbranch_execz .LBB0_132
	v_or_b32_e32 v52, 24, v22
	v_mul_lo_u32 v54, v17, v52
	v_mad_u64_u32 v[52:53], s[44:45], v16, v52, 0
	v_add3_u32 v53, v53, v6, v54
	v_lshl_add_u64 v[52:53], v[52:53], 2, v[20:21]
	global_load_dword v52, v[52:53], off
	s_and_saveexec_b64 s[44:45], s[6:7]
	s_cbranch_execz .LBB0_131
	v_lshl_add_u64 v[54:55], v[22:23], 2, v[14:15]
	global_load_dword v88, v[54:55], off offset:96

; __device__ __forceinline__ void tconv_wave(const float* __restrict__ src, int ldsrc, int k0, int nsrc0, int nvalid,
;                                            u16* __restrict__ dst, int K, int ndst0, const float* __restrict__ gain, float* smw, int lane, int permg) {
;     ...
;   for (int kb = 0; kb < 64; kb += 32) {
;     float v[32];
; #pragma unroll
;     for (int i = 0; i < 32; i++) {
;       float t = 0.f;
;       if (lane < nvalid) {
;         t = src[(size_t)(k0 + kb + i) * ldsrc + nsrc0 + lane];
;         if (gain) t *= gain[k0 + kb + i];
;       }
;       v[i] = t;
;     }
; #pragma unroll
;     for (int i = 0; i < 32; i++) smw[(kb + i) * 65 + lane] = v[i];
.LBB0_132:
	s_or_b64 exec, exec, s[42:43]
	s_and_saveexec_b64 s[42:43], s[38:39]
	s_cbranch_execz .LBB0_136
	v_or_b32_e32 v51, 25, v22
	v_mul_lo_u32 v53, v17, v51
	v_mad_u64_u32 v[54:55], s[44:45], v16, v51, 0
	v_add3_u32 v55, v55, v6, v53
	v_lshl_add_u64 v[54:55], v[54:55], 2, v[20:21]
	global_load_dword v51, v[54:55], off
	s_and_saveexec_b64 s[44:45], s[6:7]
	s_cbranch_execz .LBB0_135
	v_lshl_add_u64 v[54:55], v[22:23], 2, v[14:15]
	global_load_dword v89, v[54:55], off offset:100

; __device__ __forceinline__ void tconv_wave(const float* __restrict__ src, int ldsrc, int k0, int nsrc0, int nvalid,
;                                            u16* __restrict__ dst, int K, int ndst0, const float* __restrict__ gain, float* smw, int lane, int permg) {
;     ...
;   for (int kb = 0; kb < 64; kb += 32) {
;     float v[32];
; #pragma unroll
;     for (int i = 0; i < 32; i++) {
;       float t = 0.f;
;       if (lane < nvalid) {
;         t = src[(size_t)(k0 + kb + i) * ldsrc + nsrc0 + lane];
;         if (gain) t *= gain[k0 + kb + i];
;       }
;       v[i] = t;
;     }
; #pragma unroll
;     for (int i = 0; i < 32; i++) smw[(kb + i) * 65 + lane] = v[i];
.LBB0_136:
	s_or_b64 exec, exec, s[42:43]
	v_mov_b32_e32 v53, 0
	v_mov_b32_e32 v54, 0
	s_and_saveexec_b64 s[42:43], s[38:39]
	s_cbranch_execz .LBB0_140
	v_or_b32_e32 v54, 26, v22
	v_mul_lo_u32 v56, v17, v54
	v_mad_u64_u32 v[54:55], s[44:45], v16, v54, 0
	v_add3_u32 v55, v55, v6, v56
	v_lshl_add_u64 v[54:55], v[54:55], 2, v[20:21]
	global_load_dword v54, v[54:55], off
	s_and_saveexec_b64 s[44:45], s[6:7]
	s_cbranch_execz .LBB0_139
	v_lshl_add_u64 v[56:57], v[22:23], 2, v[14:15]
	global_load_dword v90, v[56:57], off offset:104

; __device__ __forceinline__ void tconv_wave(const float* __restrict__ src, int ldsrc, int k0, int nsrc0, int nvalid,
;                                            u16* __restrict__ dst, int K, int ndst0, const float* __restrict__ gain, float* smw, int lane, int permg) {
;     ...
;   for (int kb = 0; kb < 64; kb += 32) {
;     float v[32];
; #pragma unroll
;     for (int i = 0; i < 32; i++) {
;       float t = 0.f;
;       if (lane < nvalid) {
;         t = src[(size_t)(k0 + kb + i) * ldsrc + nsrc0 + lane];
;         if (gain) t *= gain[k0 + kb + i];
;       }
;       v[i] = t;
;     }
; #pragma unroll
;     for (int i = 0; i < 32; i++) smw[(kb + i) * 65 + lane] = v[i];
.LBB0_140:
	s_or_b64 exec, exec, s[42:43]
	s_and_saveexec_b64 s[42:43], s[38:39]
	s_cbranch_execz .LBB0_144
	v_or_b32_e32 v53, 27, v22
	v_mul_lo_u32 v55, v17, v53
	v_mad_u64_u32 v[56:57], s[44:45], v16, v53, 0
	v_add3_u32 v57, v57, v6, v55
	v_lshl_add_u64 v[56:57], v[56:57], 2, v[20:21]
	global_load_dword v53, v[56:57], off
	s_and_saveexec_b64 s[44:45], s[6:7]
	s_cbranch_execz .LBB0_143
	v_lshl_add_u64 v[56:57], v[22:23], 2, v[14:15]
	global_load_dword v91, v[56:57], off offset:108

; __device__ __forceinline__ void tconv_wave(const float* __restrict__ src, int ldsrc, int k0, int nsrc0, int nvalid,
;                                            u16* __restrict__ dst, int K, int ndst0, const float* __restrict__ gain, float* smw, int lane, int permg) {
;     ...
;   for (int kb = 0; kb < 64; kb += 32) {
;     float v[32];
; #pragma unroll
;     for (int i = 0; i < 32; i++) {
;       float t = 0.f;
;       if (lane < nvalid) {
;         t = src[(size_t)(k0 + kb + i) * ldsrc + nsrc0 + lane];
;         if (gain) t *= gain[k0 + kb + i];
;       }
;       v[i] = t;
;     }
; #pragma unroll
;     for (int i = 0; i < 32; i++) smw[(kb + i) * 65 + lane] = v[i];
.LBB0_144:
	s_or_b64 exec, exec, s[42:43]
	v_mov_b32_e32 v55, 0
	v_mov_b32_e32 v56, 0
	s_and_saveexec_b64 s[42:43], s[38:39]
	s_cbranch_execz .LBB0_148
	v_or_b32_e32 v56, 28, v22
	v_mul_lo_u32 v58, v17, v56
	v_mad_u64_u32 v[56:57], s[44:45], v16, v56, 0
	v_add3_u32 v57, v57, v6, v58
	v_lshl_add_u64 v[56:57], v[56:57], 2, v[20:21]
	global_load_dword v56, v[56:57], off
	s_and_saveexec_b64 s[44:45], s[6:7]
	s_cbranch_execz .LBB0_147
	v_lshl_add_u64 v[58:59], v[22:23], 2, v[14:15]
	global_load_dword v92, v[58:59], off offset:112

; __device__ __forceinline__ void tconv_wave(const float* __restrict__ src, int ldsrc, int k0, int nsrc0, int nvalid,
;                                            u16* __restrict__ dst, int K, int ndst0, const float* __restrict__ gain, float* smw, int lane, int permg) {
;     ...
;   for (int kb = 0; kb < 64; kb += 32) {
;     float v[32];
; #pragma unroll
;     for (int i = 0; i < 32; i++) {
;       float t = 0.f;
;       if (lane < nvalid) {
;         t = src[(size_t)(k0 + kb + i) * ldsrc + nsrc0 + lane];
;         if (gain) t *= gain[k0 + kb + i];
;       }
;       v[i] = t;
;     }
; #pragma unroll
;     for (int i = 0; i < 32; i++) smw[(kb + i) * 65 + lane] = v[i];
.LBB0_148:
	s_or_b64 exec, exec, s[42:43]
	s_and_saveexec_b64 s[42:43], s[38:39]
	s_cbranch_execz .LBB0_152
	v_or_b32_e32 v55, 29, v22
	v_mul_lo_u32 v57, v17, v55
	v_mad_u64_u32 v[58:59], s[44:45], v16, v55, 0
	v_add3_u32 v59, v59, v6, v57
	v_lshl_add_u64 v[58:59], v[58:59], 2, v[20:21]
	global_load_dword v55, v[58:59], off
	s_and_saveexec_b64 s[44:45], s[6:7]
	s_cbranch_execz .LBB0_151
	v_lshl_add_u64 v[58:59], v[22:23], 2, v[14:15]
	global_load_dword v93, v[58:59], off offset:116

; __device__ __forceinline__ void tconv_wave(const float* __restrict__ src, int ldsrc, int k0, int nsrc0, int nvalid,
;                                            u16* __restrict__ dst, int K, int ndst0, const float* __restrict__ gain, float* smw, int lane, int permg) {
;     ...
;   for (int kb = 0; kb < 64; kb += 32) {
;     float v[32];
; #pragma unroll
;     for (int i = 0; i < 32; i++) {
;       float t = 0.f;
;       if (lane < nvalid) {
;         t = src[(size_t)(k0 + kb + i) * ldsrc + nsrc0 + lane];
;         if (gain) t *= gain[k0 + kb + i];
;       }
;       v[i] = t;
;     }
; #pragma unroll
;     for (int i = 0; i < 32; i++) smw[(kb + i) * 65 + lane] = v[i];
.LBB0_152:
	s_or_b64 exec, exec, s[42:43]
	v_mov_b32_e32 v57, 0
	v_mov_b32_e32 v58, 0
	s_and_saveexec_b64 s[42:43], s[38:39]
	s_cbranch_execz .LBB0_156
	v_or_b32_e32 v58, 30, v22
	v_mul_lo_u32 v60, v17, v58
	v_mad_u64_u32 v[58:59], s[44:45], v16, v58, 0
	v_add3_u32 v59, v59, v6, v60
	v_lshl_add_u64 v[58:59], v[58:59], 2, v[20:21]
	global_load_dword v58, v[58:59], off
	s_and_saveexec_b64 s[44:45], s[6:7]
	s_cbranch_execz .LBB0_155
	v_lshl_add_u64 v[60:61], v[22:23], 2, v[14:15]
	global_load_dword v94, v[60:61], off offset:120

; __device__ __forceinline__ void tconv_wave(const float* __restrict__ src, int ldsrc, int k0, int nsrc0, int nvalid,
;                                            u16* __restrict__ dst, int K, int ndst0, const float* __restrict__ gain, float* smw, int lane, int permg) {
;     ...
;   for (int kb = 0; kb < 64; kb += 32) {
;     float v[32];
; #pragma unroll
;     for (int i = 0; i < 32; i++) {
;       float t = 0.f;
;       if (lane < nvalid) {
;         t = src[(size_t)(k0 + kb + i) * ldsrc + nsrc0 + lane];
;         if (gain) t *= gain[k0 + kb + i];
;       }
;       v[i] = t;
;     }
; #pragma unroll
;     for (int i = 0; i < 32; i++) smw[(kb + i) * 65 + lane] = v[i];
.LBB0_156:
	s_or_b64 exec, exec, s[42:43]
	s_and_saveexec_b64 s[42:43], s[38:39]
	s_cbranch_execz .LBB0_31
	v_or_b32_e32 v57, 31, v22
	v_mul_lo_u32 v59, v17, v57
	v_mad_u64_u32 v[60:61], s[44:45], v16, v57, 0
	v_add3_u32 v61, v61, v6, v59
	v_lshl_add_u64 v[60:61], v[60:61], 2, v[20:21]
	global_load_dword v57, v[60:61], off
	s_and_saveexec_b64 s[44:45], s[6:7]
	s_cbranch_execz .LBB0_30
	v_lshl_add_u64 v[22:23], v[22:23], 2, v[14:15]
	global_load_dword v95, v[22:23], off offset:124
	s_branch .LBB0_30

; __device__ void phase2(const Params& p, unsigned char* smem) {
;     ...
;         P2_SCORE(cA0, cB0, c * 4 + 0)
;         P2_SCORE(cA1, cB1, c * 4 + 1)
;         P2_SCORE(cA2, cB2, c * 4 + 2)
;         P2_SCORE(cA3, cB3, c * 4 + 3)
.LBB0_550:
	s_or_b64 exec, exec, s[48:49]
	s_and_b64 s[36:37], exec, s[36:37]
	s_or_b64 s[40:41], s[36:37], s[40:41]
	v_mfma_f32_16x16x32_bf16 v[160:163], v[38:41], v[34:37], 0
	v_add_u32_e32 v165, 0xffff0000, v139
	v_lshl_add_u64 v[142:143], v[142:143], 0, s[60:61]
	v_mfma_f32_16x16x32_bf16 v[160:163], v[42:45], v[30:33], v[160:163]
	s_nop 7
	v_max_f32_e32 v161, 0, v161
	v_max_f32_e32 v160, 0, v160
	v_mul_f32_e32 v161, v47, v161
	v_max_f32_e32 v162, 0, v162
	v_fmac_f32_e32 v161, v46, v160
	v_max_f32_e32 v163, 0, v163
	v_fmac_f32_e32 v161, v48, v162
	v_fmac_f32_e32 v161, v49, v163
	v_mov_b32_e32 v160, v161
	s_nop 1
	v_permlane16_swap_b32_e32 v161, v160
	v_add_f32_e32 v164, v161, v160
	v_mfma_f32_16x16x32_bf16 v[160:163], v[50:53], v[34:37], 0
	v_cvt_f16_f32_e32 v164, v164
	v_bfe_i32 v166, v164, 15, 1
	v_mfma_f32_16x16x32_bf16 v[160:163], v[54:57], v[30:33], v[160:163]
	v_bitop3_b16 v164, v166, v164, s71 bitop3:0x36
	ds_write_b16 v165, v164
	s_nop 5
	v_max_f32_e32 v161, 0, v161
	v_max_f32_e32 v160, 0, v160
	v_mul_f32_e32 v161, v59, v161
	v_fmac_f32_e32 v161, v58, v160
	v_max_f32_e32 v160, 0, v162
	v_fmac_f32_e32 v161, v60, v160
	v_max_f32_e32 v160, 0, v163
	v_fmac_f32_e32 v161, v61, v160
	v_mov_b32_e32 v160, v161
	s_nop 1
	v_permlane16_swap_b32_e32 v161, v160
	v_add_f32_e32 v160, v161, v160
	v_cvt_f16_f32_e32 v167, v160
	v_mfma_f32_16x16x32_bf16 v[160:163], v[62:65], v[34:37], 0
	v_bfe_i32 v164, v167, 15, 1
	s_nop 0
	v_bitop3_b16 v164, v164, v167, s71 bitop3:0x36
	v_mfma_f32_16x16x32_bf16 v[34:37], v[74:77], v[34:37], 0
	v_mfma_f32_16x16x32_bf16 v[160:163], v[66:69], v[30:33], v[160:163]
	v_mfma_f32_16x16x32_bf16 v[30:33], v[78:81], v[30:33], v[34:37]
	s_nop 6
	s_nop 0
	v_max_f32_e32 v31, 0, v31
	v_max_f32_e32 v30, 0, v30
	v_mul_f32_e32 v31, v83, v31
	v_fmac_f32_e32 v31, v82, v30
	v_max_f32_e32 v30, 0, v32
	v_fmac_f32_e32 v31, v84, v30
	v_max_f32_e32 v30, 0, v33
	v_fmac_f32_e32 v31, v85, v30
	v_mov_b32_e32 v30, v31
	s_nop 1
	v_permlane16_swap_b32_e32 v31, v30
	v_add_f32_e32 v30, v31, v30
	v_cvt_f16_f32_e32 v34, v30
	v_mfma_f32_16x16x32_bf16 v[30:33], v[38:41], v[26:29], 0
	v_max_f32_e32 v161, 0, v161
	v_max_f32_e32 v160, 0, v160
	v_mfma_f32_16x16x32_bf16 v[30:33], v[42:45], v[22:25], v[30:33]
	v_mul_f32_e32 v161, v71, v161
	v_fmac_f32_e32 v161, v70, v160
	v_max_f32_e32 v160, 0, v162
	v_fmac_f32_e32 v161, v72, v160
	s_nop 2
	s_nop 0
	v_max_f32_e32 v31, 0, v31
	v_max_f32_e32 v30, 0, v30
	v_mul_f32_e32 v31, v47, v31
	v_fmac_f32_e32 v31, v46, v30
	v_max_f32_e32 v30, 0, v32
	v_fmac_f32_e32 v31, v48, v30
	v_max_f32_e32 v30, 0, v33
	v_fmac_f32_e32 v31, v49, v30
	v_mov_b32_e32 v30, v31
	s_nop 1
	v_permlane16_swap_b32_e32 v31, v30
	v_add_f32_e32 v30, v31, v30
	v_cvt_f16_f32_e32 v36, v30
	v_mfma_f32_16x16x32_bf16 v[30:33], v[50:53], v[26:29], 0
	v_max_f32_e32 v160, 0, v163
	v_fmac_f32_e32 v161, v73, v160
	v_mfma_f32_16x16x32_bf16 v[30:33], v[54:57], v[22:25], v[30:33]
	v_mov_b32_e32 v160, v161
	s_nop 1
	v_permlane16_swap_b32_e32 v161, v160
	v_add_f32_e32 v160, v161, v160
	v_cvt_f16_f32_e32 v160, v160
	s_nop 1
	v_max_f32_e32 v31, 0, v31
	v_max_f32_e32 v30, 0, v30
	v_mul_f32_e32 v31, v59, v31
	v_fmac_f32_e32 v31, v58, v30
	v_max_f32_e32 v30, 0, v32
	v_fmac_f32_e32 v31, v60, v30
	v_max_f32_e32 v30, 0, v33
	v_fmac_f32_e32 v31, v61, v30
	v_add_u32_e32 v161, 0xffff8000, v139
	v_mov_b32_e32 v30, v31
	ds_write_b16 v161, v164
	v_bfe_i32 v161, v160, 15, 1
	s_nop 0
	v_permlane16_swap_b32_e32 v31, v30
	v_bitop3_b16 v35, v161, v160, s71 bitop3:0x36
	ds_write_b16 v139, v35
	v_bfe_i32 v35, v34, 15, 1
	v_add_f32_e32 v30, v31, v30
	v_bitop3_b16 v34, v35, v34, s71 bitop3:0x36
	v_cvt_f16_f32_e32 v35, v30
	v_mfma_f32_16x16x32_bf16 v[30:33], v[62:65], v[26:29], 0
	ds_write_b16 v139, v34 offset:32768
	v_bfe_i32 v34, v36, 15, 1
	v_mfma_f32_16x16x32_bf16 v[26:29], v[74:77], v[26:29], 0
	v_bitop3_b16 v34, v34, v36, s71 bitop3:0x36
	v_add_u32_e32 v36, 0xffff0020, v139
	ds_write_b16 v36, v34
	v_mfma_f32_16x16x32_bf16 v[30:33], v[66:69], v[22:25], v[30:33]
	v_bfe_i32 v34, v35, 15, 1
	s_nop 0
	v_bitop3_b16 v34, v34, v35, s71 bitop3:0x36
	v_mfma_f32_16x16x32_bf16 v[22:25], v[78:81], v[22:25], v[26:29]
	s_nop 4
	s_nop 1
	s_nop 0
	v_max_f32_e32 v23, 0, v23
	v_max_f32_e32 v22, 0, v22
	v_mul_f32_e32 v23, v83, v23
	v_fmac_f32_e32 v23, v82, v22
	v_max_f32_e32 v22, 0, v24
	v_fmac_f32_e32 v23, v84, v22
	v_max_f32_e32 v22, 0, v25
	v_fmac_f32_e32 v23, v85, v22
	v_mov_b32_e32 v22, v23
	s_nop 1
	v_permlane16_swap_b32_e32 v23, v22
	v_add_f32_e32 v22, v23, v22
	v_cvt_f16_f32_e32 v26, v22
	v_mfma_f32_16x16x32_bf16 v[22:25], v[38:41], v[18:21], 0
	v_max_f32_e32 v31, 0, v31
	v_max_f32_e32 v30, 0, v30
	v_mfma_f32_16x16x32_bf16 v[22:25], v[42:45], v[14:17], v[22:25]
	v_mul_f32_e32 v31, v71, v31
	v_fmac_f32_e32 v31, v70, v30
	v_max_f32_e32 v30, 0, v32
	v_fmac_f32_e32 v31, v72, v30
	s_nop 2
	s_nop 0
	v_max_f32_e32 v23, 0, v23
	v_max_f32_e32 v22, 0, v22
	v_mul_f32_e32 v23, v47, v23
	v_fmac_f32_e32 v23, v46, v22
	v_max_f32_e32 v22, 0, v24
	v_fmac_f32_e32 v23, v48, v22
	v_max_f32_e32 v22, 0, v25
	v_fmac_f32_e32 v23, v49, v22
	v_mov_b32_e32 v22, v23
	s_nop 1
	v_permlane16_swap_b32_e32 v23, v22
	v_add_f32_e32 v22, v23, v22
	v_cvt_f16_f32_e32 v28, v22
	v_mfma_f32_16x16x32_bf16 v[22:25], v[50:53], v[18:21], 0
	v_max_f32_e32 v30, 0, v33
	v_fmac_f32_e32 v31, v73, v30
	v_mfma_f32_16x16x32_bf16 v[22:25], v[54:57], v[14:17], v[22:25]
	v_mov_b32_e32 v30, v31
	s_nop 1
	v_permlane16_swap_b32_e32 v31, v30
	v_add_f32_e32 v30, v31, v30
	v_cvt_f16_f32_e32 v30, v30
	s_nop 1
	v_max_f32_e32 v23, 0, v23
	v_max_f32_e32 v22, 0, v22
	v_mul_f32_e32 v23, v59, v23
	v_fmac_f32_e32 v23, v58, v22
	v_max_f32_e32 v22, 0, v24
	v_fmac_f32_e32 v23, v60, v22
	v_max_f32_e32 v22, 0, v25
	v_fmac_f32_e32 v23, v61, v22
	v_add_u32_e32 v31, 0xffff8020, v139
	v_mov_b32_e32 v22, v23
	ds_write_b16 v31, v34
	v_bfe_i32 v31, v30, 15, 1
	s_nop 0
	v_permlane16_swap_b32_e32 v23, v22
	v_bitop3_b16 v27, v31, v30, s71 bitop3:0x36
	ds_write_b16 v139, v27 offset:32
	v_bfe_i32 v27, v26, 15, 1
	v_add_f32_e32 v22, v23, v22
	v_bitop3_b16 v26, v27, v26, s71 bitop3:0x36
	v_cvt_f16_f32_e32 v27, v22
	v_mfma_f32_16x16x32_bf16 v[22:25], v[62:65], v[18:21], 0
	ds_write_b16 v139, v26 offset:32800
	v_bfe_i32 v26, v28, 15, 1
	s_waitcnt vmcnt(0)
; __device__ void phase2(const Params& p, unsigned char* smem) {
;     ...
;         P2_SCORE(cA0, cB0, c * 4 + 0)
;         P2_SCORE(cA1, cB1, c * 4 + 1)
;         P2_SCORE(cA2, cB2, c * 4 + 2)
;         P2_SCORE(cA3, cB3, c * 4 + 3)
	v_mov_b64_e32 v[34:35], v[106:107]
	v_mfma_f32_16x16x32_bf16 v[18:21], v[74:77], v[18:21], 0
	v_bitop3_b16 v26, v26, v28, s71 bitop3:0x36
	v_add_u32_e32 v28, 0xffff0040, v139
	ds_write_b16 v28, v26
	v_mfma_f32_16x16x32_bf16 v[22:25], v[66:69], v[14:17], v[22:25]
	v_bfe_i32 v26, v27, 15, 1
	v_mov_b64_e32 v[30:31], v[98:99]
	v_bitop3_b16 v26, v26, v27, s71 bitop3:0x36
	v_mfma_f32_16x16x32_bf16 v[14:17], v[78:81], v[14:17], v[18:21]
	v_mov_b64_e32 v[36:37], v[108:109]
	s_nop 3
	v_max_f32_e32 v23, 0, v23
	v_max_f32_e32 v22, 0, v22
	s_nop 0
	v_max_f32_e32 v15, 0, v15
	v_max_f32_e32 v14, 0, v14
	v_mul_f32_e32 v15, v83, v15
	v_fmac_f32_e32 v15, v82, v14
	v_max_f32_e32 v14, 0, v16
	v_fmac_f32_e32 v15, v84, v14
	v_max_f32_e32 v14, 0, v17
	v_fmac_f32_e32 v15, v85, v14
	v_mov_b32_e32 v14, v15
	s_nop 1
	v_permlane16_swap_b32_e32 v15, v14
	v_add_f32_e32 v14, v15, v14
	v_cvt_f16_f32_e32 v18, v14
	v_mfma_f32_16x16x32_bf16 v[14:17], v[38:41], v[10:13], 0
	v_mul_f32_e32 v23, v71, v23
	v_fmac_f32_e32 v23, v70, v22
	v_mfma_f32_16x16x32_bf16 v[14:17], v[42:45], v[6:9], v[14:17]
	v_max_f32_e32 v22, 0, v24
	v_fmac_f32_e32 v23, v72, v22
	v_max_f32_e32 v22, 0, v25
	v_fmac_f32_e32 v23, v73, v22
	s_nop 2
	s_nop 0
	v_max_f32_e32 v15, 0, v15
	v_max_f32_e32 v14, 0, v14
	v_mul_f32_e32 v15, v47, v15
	v_fmac_f32_e32 v15, v46, v14
	v_max_f32_e32 v14, 0, v16
	v_fmac_f32_e32 v15, v48, v14
	v_max_f32_e32 v14, 0, v17
	v_fmac_f32_e32 v15, v49, v14
	v_mov_b32_e32 v14, v15
	s_nop 1
	v_permlane16_swap_b32_e32 v15, v14
	v_add_f32_e32 v14, v15, v14
	v_cvt_f16_f32_e32 v20, v14
	v_mfma_f32_16x16x32_bf16 v[14:17], v[50:53], v[10:13], 0
	v_mov_b32_e32 v22, v23
	s_nop 1
	v_permlane16_swap_b32_e32 v23, v22
	v_mfma_f32_16x16x32_bf16 v[14:17], v[54:57], v[6:9], v[14:17]
	v_add_f32_e32 v22, v23, v22
	v_cvt_f16_f32_e32 v22, v22
	v_add_u32_e32 v23, 0xffff8040, v139
	ds_write_b16 v23, v26
	v_bfe_i32 v23, v22, 15, 1
	s_nop 3
	v_max_f32_e32 v15, 0, v15
	v_max_f32_e32 v14, 0, v14
	v_mul_f32_e32 v15, v59, v15
	v_fmac_f32_e32 v15, v58, v14
	v_max_f32_e32 v14, 0, v16
	v_fmac_f32_e32 v15, v60, v14
	v_max_f32_e32 v14, 0, v17
	v_fmac_f32_e32 v15, v61, v14
	v_mov_b32_e32 v14, v15
	v_bitop3_b16 v19, v23, v22, s71 bitop3:0x36
	s_nop 0
	v_permlane16_swap_b32_e32 v15, v14
	ds_write_b16 v139, v19 offset:64
	v_bfe_i32 v19, v18, 15, 1
	v_add_f32_e32 v14, v15, v14
	v_bitop3_b16 v18, v19, v18, s71 bitop3:0x36
	ds_write_b16 v139, v18 offset:32832
	v_bfe_i32 v18, v20, 15, 1
	v_cvt_f16_f32_e32 v19, v14
	v_bitop3_b16 v14, v18, v20, s71 bitop3:0x36
	v_add_u32_e32 v15, 0xffff0060, v139
	ds_write_b16 v15, v14
	v_mfma_f32_16x16x32_bf16 v[14:17], v[62:65], v[10:13], 0
	v_bfe_i32 v18, v19, 15, 1
	v_mov_b64_e32 v[26:27], v[90:91]
	v_bitop3_b16 v18, v18, v19, s71 bitop3:0x36
	v_mfma_f32_16x16x32_bf16 v[10:13], v[74:77], v[10:13], 0
	v_add_u32_e32 v19, 0xffff8060, v139
	ds_write_b16 v19, v18
	v_mov_b64_e32 v[22:23], v[86:87]
	v_mfma_f32_16x16x32_bf16 v[14:17], v[66:69], v[6:9], v[14:17]
	v_mov_b64_e32 v[18:19], v[114:115]
	v_mov_b64_e32 v[32:33], v[100:101]
	v_mov_b64_e32 v[28:29], v[92:93]
	v_mfma_f32_16x16x32_bf16 v[6:9], v[78:81], v[6:9], v[10:13]
	v_mov_b64_e32 v[24:25], v[88:89]
	s_nop 2
	v_max_f32_e32 v15, 0, v15
	v_max_f32_e32 v14, 0, v14
	v_mul_f32_e32 v15, v71, v15
	s_nop 0
	v_max_f32_e32 v7, 0, v7
	v_fmac_f32_e32 v15, v70, v14
	v_max_f32_e32 v6, 0, v6
	v_mul_f32_e32 v7, v83, v7
	v_max_f32_e32 v14, 0, v16
	v_fmac_f32_e32 v7, v82, v6
	v_fmac_f32_e32 v15, v72, v14
	v_max_f32_e32 v6, 0, v8
	v_max_f32_e32 v14, 0, v17
	v_fmac_f32_e32 v7, v84, v6
	v_fmac_f32_e32 v15, v73, v14
	v_max_f32_e32 v6, 0, v9
	v_mov_b32_e32 v14, v15
	v_fmac_f32_e32 v7, v85, v6
	s_nop 0
	v_permlane16_swap_b32_e32 v15, v14
	v_mov_b32_e32 v6, v7
	v_add_f32_e32 v14, v15, v14
	s_nop 0
	v_permlane16_swap_b32_e32 v7, v6
	v_cvt_f16_f32_e32 v14, v14
	v_add_f32_e32 v6, v7, v6
	v_cvt_f16_f32_e32 v6, v6
	v_bfe_i32 v7, v14, 15, 1
	v_mov_b64_e32 v[10:11], v[102:103]
	v_bitop3_b16 v7, v7, v14, s71 bitop3:0x36
	ds_write_b16 v139, v7 offset:96
	v_bfe_i32 v7, v6, 15, 1
	v_mov_b64_e32 v[14:15], v[110:111]
	v_bitop3_b16 v6, v7, v6, s71 bitop3:0x36
	ds_write_b16 v139, v6 offset:32864
	v_mov_b64_e32 v[6:7], v[94:95]
	v_add_u32_e32 v139, 0x400, v139
	v_mov_b64_e32 v[20:21], v[116:117]
	v_mov_b64_e32 v[16:17], v[112:113]
	v_mov_b64_e32 v[12:13], v[104:105]
	v_mov_b64_e32 v[8:9], v[96:97]
	s_andn2_b64 exec, exec, s[40:41]
	s_cbranch_execz .LBB0_553
